# conv_a2 1/|k| loop: four items per trip, all 28 loads requested before the four reductions (counted waits); one-item loop kept as remainder path
# baseline (speedup 1.0000x reference)
.Linv_top:
	s_mul_i32 s100, s87, 3
	v_add_u32_e32 v109, s100, v40
	s_mov_b32 s0, 0x17ffff
	v_cmp_ge_i32_e32 vcc, s0, v109
	s_nop 3
	s_cmp_eq_u64 vcc, exec
	s_cbranch_scc0 .Linv_test
	v_mov_b32_e32 v109, v40
	v_ashrrev_i32_e32 v4, 3, v109
	v_mul_hi_i32 v0, v4, s85
	v_lshrrev_b32_e32 v1, 31, v0
	v_add_u32_e32 v19, v0, v1
	v_mul_lo_u32 v0, v19, 6
	v_sub_u32_e32 v12, v4, v0
	v_lshl_or_b32 v14, v12, 6, v18
	v_mov_b64_e32 v[0:1], s[92:93]
	v_mad_i64_i32 v[0:1], s[0:1], v19, s31, v[0:1]
	v_ashrrev_i32_e32 v15, 31, v14
	v_lshl_add_u64 v[8:9], v[14:15], 1, v[0:1]
	v_add_co_u32_e32 v0, vcc, 0x11400000, v8
	s_mov_b32 s0, 0x18000
	s_nop 0
	v_addc_co_u32_e32 v1, vcc, 0, v9, vcc
	global_load_dwordx4 v[42:45], v[0:1], off offset:768
	v_cmp_gt_i32_e32 vcc, s0, v4
	s_mov_b64 s[0:1], 0x11400300
	v_lshl_add_u64 v[16:17], v[8:9], 0, s[0:1]
	v_cndmask_b32_e32 v5, v243, v244, vcc
	v_and_b32_e32 v6, v5, v19
	v_cmp_ne_u32_e32 vcc, 0, v6
	v_mov_b32_e32 v46, 0
	v_mov_b32_e32 v47, 0
	v_mov_b32_e32 v48, 0
	v_mov_b32_e32 v49, 0
	s_and_saveexec_b64 s[12:13], vcc
	global_load_dwordx4 v[46:49], v[16:17], off offset:-2304
	s_or_b64 exec, exec, s[12:13]
	v_cmp_ne_u32_e32 vcc, v6, v5
	v_mov_b32_e32 v52, 0
	v_mov_b32_e32 v53, 0
	v_mov_b32_e32 v54, 0
	v_mov_b32_e32 v55, 0
	s_and_saveexec_b64 s[12:13], vcc
	global_load_dwordx4 v[52:55], v[16:17], off offset:2304
	s_or_b64 exec, exec, s[12:13]
	v_readlane_b32 s0, v254, 50
	v_readlane_b32 s1, v254, 51
	v_lshlrev_b64 v[2:3], 2, v[14:15]
	v_mov_b32_e32 v41, v19
	v_lshl_add_u64 v[10:11], s[0:1], 0, v[2:3]
	global_load_dwordx4 v[56:59], v[10:11], off offset:1552
	global_load_dwordx4 v[60:63], v[10:11], off offset:1536
	v_readlane_b32 s0, v254, 54
	v_readlane_b32 s1, v254, 55
	v_mov_b32_e32 v98, v12
	s_nop 0
	v_lshl_add_u64 v[20:21], s[0:1], 0, v[2:3]
	global_load_dwordx4 v[64:67], v[20:21], off offset:16
	global_load_dwordx4 v[68:71], v[20:21], off
	v_add_u32_e32 v109, s87, v109
	v_ashrrev_i32_e32 v4, 3, v109
	v_mul_hi_i32 v0, v4, s85
	v_lshrrev_b32_e32 v1, 31, v0
	v_add_u32_e32 v19, v0, v1
	v_mul_lo_u32 v0, v19, 6
	v_sub_u32_e32 v12, v4, v0
	v_lshl_or_b32 v14, v12, 6, v18
	v_mov_b64_e32 v[0:1], s[92:93]
	v_mad_i64_i32 v[0:1], s[0:1], v19, s31, v[0:1]
	v_ashrrev_i32_e32 v15, 31, v14
	v_lshl_add_u64 v[8:9], v[14:15], 1, v[0:1]
	v_add_co_u32_e32 v0, vcc, 0x11400000, v8
	s_mov_b32 s0, 0x18000
	s_nop 0
	v_addc_co_u32_e32 v1, vcc, 0, v9, vcc
	global_load_dwordx4 v[76:79], v[0:1], off offset:768
	v_cmp_gt_i32_e32 vcc, s0, v4
	s_mov_b64 s[0:1], 0x11400300
	v_lshl_add_u64 v[16:17], v[8:9], 0, s[0:1]
	v_cndmask_b32_e32 v5, v243, v244, vcc
	v_and_b32_e32 v6, v5, v19
	v_cmp_ne_u32_e32 vcc, 0, v6
	v_mov_b32_e32 v80, 0
	v_mov_b32_e32 v81, 0
	v_mov_b32_e32 v82, 0
	v_mov_b32_e32 v83, 0
	s_and_saveexec_b64 s[12:13], vcc
	global_load_dwordx4 v[80:83], v[16:17], off offset:-2304
	s_or_b64 exec, exec, s[12:13]
	v_cmp_ne_u32_e32 vcc, v6, v5
	v_mov_b32_e32 v84, 0
	v_mov_b32_e32 v85, 0
	v_mov_b32_e32 v86, 0
	v_mov_b32_e32 v87, 0
	s_and_saveexec_b64 s[12:13], vcc
	global_load_dwordx4 v[84:87], v[16:17], off offset:2304
	s_or_b64 exec, exec, s[12:13]
	v_readlane_b32 s0, v254, 50
	v_readlane_b32 s1, v254, 51
	v_lshlrev_b64 v[2:3], 2, v[14:15]
	v_mov_b32_e32 v50, v19
	v_lshl_add_u64 v[10:11], s[0:1], 0, v[2:3]
	global_load_dwordx4 v[88:91], v[10:11], off offset:1552
	global_load_dwordx4 v[92:95], v[10:11], off offset:1536
	v_readlane_b32 s0, v254, 54
	v_readlane_b32 s1, v254, 55
	v_mov_b32_e32 v100, v12
	s_nop 0
	v_lshl_add_u64 v[20:21], s[0:1], 0, v[2:3]
	global_load_dwordx4 v[114:117], v[20:21], off offset:16
	global_load_dwordx4 v[122:125], v[20:21], off
	v_add_u32_e32 v109, s87, v109
	v_ashrrev_i32_e32 v4, 3, v109
	v_mul_hi_i32 v0, v4, s85
	v_lshrrev_b32_e32 v1, 31, v0
	v_add_u32_e32 v19, v0, v1
	v_mul_lo_u32 v0, v19, 6
	v_sub_u32_e32 v12, v4, v0
	v_lshl_or_b32 v14, v12, 6, v18
	v_mov_b64_e32 v[0:1], s[92:93]
	v_mad_i64_i32 v[0:1], s[0:1], v19, s31, v[0:1]
	v_ashrrev_i32_e32 v15, 31, v14
	v_lshl_add_u64 v[8:9], v[14:15], 1, v[0:1]
	v_add_co_u32_e32 v0, vcc, 0x11400000, v8
	s_mov_b32 s0, 0x18000
	s_nop 0
	v_addc_co_u32_e32 v1, vcc, 0, v9, vcc
	global_load_dwordx4 v[126:129], v[0:1], off offset:768
	v_cmp_gt_i32_e32 vcc, s0, v4
	s_mov_b64 s[0:1], 0x11400300
	v_lshl_add_u64 v[16:17], v[8:9], 0, s[0:1]
	v_cndmask_b32_e32 v5, v243, v244, vcc
	v_and_b32_e32 v6, v5, v19
	v_cmp_ne_u32_e32 vcc, 0, v6
	v_mov_b32_e32 v130, 0
	v_mov_b32_e32 v131, 0
	v_mov_b32_e32 v132, 0
	v_mov_b32_e32 v133, 0
	s_and_saveexec_b64 s[12:13], vcc
	global_load_dwordx4 v[130:133], v[16:17], off offset:-2304
	s_or_b64 exec, exec, s[12:13]
	v_cmp_ne_u32_e32 vcc, v6, v5
	v_mov_b32_e32 v164, 0
	v_mov_b32_e32 v165, 0
	v_mov_b32_e32 v166, 0
	v_mov_b32_e32 v167, 0
	s_and_saveexec_b64 s[12:13], vcc
	global_load_dwordx4 v[164:167], v[16:17], off offset:2304
	s_or_b64 exec, exec, s[12:13]
	v_readlane_b32 s0, v254, 50
	v_readlane_b32 s1, v254, 51
	v_lshlrev_b64 v[2:3], 2, v[14:15]
	v_mov_b32_e32 v72, v19
	v_lshl_add_u64 v[10:11], s[0:1], 0, v[2:3]
	global_load_dwordx4 v[168:171], v[10:11], off offset:1552
	global_load_dwordx4 v[172:175], v[10:11], off offset:1536
	v_readlane_b32 s0, v254, 54
	v_readlane_b32 s1, v254, 55
	v_mov_b32_e32 v103, v12
	s_nop 0
	v_lshl_add_u64 v[20:21], s[0:1], 0, v[2:3]
	global_load_dwordx4 v[176:179], v[20:21], off offset:16
	global_load_dwordx4 v[180:183], v[20:21], off
	v_add_u32_e32 v109, s87, v109
	v_ashrrev_i32_e32 v4, 3, v109
	v_mul_hi_i32 v0, v4, s85
	v_lshrrev_b32_e32 v1, 31, v0
	v_add_u32_e32 v19, v0, v1
	v_mul_lo_u32 v0, v19, 6
	v_sub_u32_e32 v12, v4, v0
	v_lshl_or_b32 v14, v12, 6, v18
	v_mov_b64_e32 v[0:1], s[92:93]
	v_mad_i64_i32 v[0:1], s[0:1], v19, s31, v[0:1]
	v_ashrrev_i32_e32 v15, 31, v14
	v_lshl_add_u64 v[8:9], v[14:15], 1, v[0:1]
	v_add_co_u32_e32 v0, vcc, 0x11400000, v8
	s_mov_b32 s0, 0x18000
	s_nop 0
	v_addc_co_u32_e32 v1, vcc, 0, v9, vcc
	global_load_dwordx4 v[196:199], v[0:1], off offset:768
	v_cmp_gt_i32_e32 vcc, s0, v4
	s_mov_b64 s[0:1], 0x11400300
	v_lshl_add_u64 v[16:17], v[8:9], 0, s[0:1]
	v_cndmask_b32_e32 v5, v243, v244, vcc
	v_and_b32_e32 v6, v5, v19
	v_cmp_ne_u32_e32 vcc, 0, v6
	v_mov_b32_e32 v200, 0
	v_mov_b32_e32 v201, 0
	v_mov_b32_e32 v202, 0
	v_mov_b32_e32 v203, 0
	s_and_saveexec_b64 s[12:13], vcc
	global_load_dwordx4 v[200:203], v[16:17], off offset:-2304
	s_or_b64 exec, exec, s[12:13]
	v_cmp_ne_u32_e32 vcc, v6, v5
	v_mov_b32_e32 v204, 0
	v_mov_b32_e32 v205, 0
	v_mov_b32_e32 v206, 0
	v_mov_b32_e32 v207, 0
	s_and_saveexec_b64 s[12:13], vcc
	global_load_dwordx4 v[204:207], v[16:17], off offset:2304
	s_or_b64 exec, exec, s[12:13]
	v_readlane_b32 s0, v254, 50
	v_readlane_b32 s1, v254, 51
	v_lshlrev_b64 v[2:3], 2, v[14:15]
	v_mov_b32_e32 v75, v19
	v_lshl_add_u64 v[10:11], s[0:1], 0, v[2:3]
	global_load_dwordx4 v[208:211], v[10:11], off offset:1552
	global_load_dwordx4 v[212:215], v[10:11], off offset:1536
	v_readlane_b32 s0, v254, 54
	v_readlane_b32 s1, v254, 55
	v_mov_b32_e32 v107, v12
	s_nop 0
	v_lshl_add_u64 v[20:21], s[0:1], 0, v[2:3]
	global_load_dwordx4 v[216:219], v[20:21], off offset:16
	global_load_dwordx4 v[220:223], v[20:21], off
	v_add_u32_e32 v109, s87, v109
	s_waitcnt vmcnt(21)
	v_cvt_f32_f16_e32 v20, v52
	v_cvt_f32_f16_sdwa v31, v52 dst_sel:DWORD dst_unused:UNUSED_PAD src0_sel:WORD_1
	v_cvt_f32_f16_e32 v32, v53
	v_cvt_f32_f16_sdwa v33, v53 dst_sel:DWORD dst_unused:UNUSED_PAD src0_sel:WORD_1
	v_cvt_f32_f16_e32 v34, v54
	v_cvt_f32_f16_sdwa v35, v54 dst_sel:DWORD dst_unused:UNUSED_PAD src0_sel:WORD_1
	v_cvt_f32_f16_e32 v36, v55
	v_cvt_f32_f16_sdwa v37, v55 dst_sel:DWORD dst_unused:UNUSED_PAD src0_sel:WORD_1
	v_cvt_f32_f16_e32 v13, v46
	v_cvt_f32_f16_sdwa v24, v46 dst_sel:DWORD dst_unused:UNUSED_PAD src0_sel:WORD_1
	v_cvt_f32_f16_e32 v25, v47
	v_cvt_f32_f16_sdwa v26, v47 dst_sel:DWORD dst_unused:UNUSED_PAD src0_sel:WORD_1
	v_cvt_f32_f16_e32 v27, v48
	v_cvt_f32_f16_sdwa v28, v48 dst_sel:DWORD dst_unused:UNUSED_PAD src0_sel:WORD_1
	v_cvt_f32_f16_e32 v29, v49
	v_cvt_f32_f16_sdwa v30, v49 dst_sel:DWORD dst_unused:UNUSED_PAD src0_sel:WORD_1
	v_add_f32_e32 v6, v13, v20
	v_fma_mix_f32 v6, v6, s76, -v42 op_sel_hi:[0,0,1]
	v_fma_mix_f32 v13, v60, v6, v42 op_sel_hi:[0,0,1]
	v_add_f32_e32 v14, v24, v31
	v_fma_mix_f32 v14, v14, s76, -v42 op_sel:[0,0,1] op_sel_hi:[0,0,1]
	v_fma_mix_f32 v0, v61, v14, v42 op_sel:[0,0,1] op_sel_hi:[0,0,1]
	v_mul_f32_e32 v0, v69, v0
	v_mul_f32_e32 v13, v68, v13
	v_mul_f32_e32 v0, v0, v0
	v_fmac_f32_e32 v0, v13, v13
	v_add_f32_e32 v13, v25, v32
	v_fma_mix_f32 v13, v13, s76, -v43 op_sel_hi:[0,0,1]
	v_fma_mix_f32 v13, v62, v13, v43 op_sel_hi:[0,0,1]
	v_mul_f32_e32 v13, v70, v13
	v_fmac_f32_e32 v0, v13, v13
	v_add_f32_e32 v13, v26, v33
	v_fma_mix_f32 v13, v13, s76, -v43 op_sel:[0,0,1] op_sel_hi:[0,0,1]
	v_fma_mix_f32 v1, v13, v63, v43 op_sel:[0,0,1] op_sel_hi:[0,0,1]
	v_mul_f32_e32 v1, v71, v1
	v_fmac_f32_e32 v0, v1, v1
	v_add_f32_e32 v1, v27, v34
	v_fma_mix_f32 v1, v1, s76, -v44 op_sel_hi:[0,0,1]
	v_fma_mix_f32 v1, v1, v56, v44 op_sel_hi:[0,0,1]
	v_mul_f32_e32 v1, v64, v1
	v_fmac_f32_e32 v0, v1, v1
	v_add_f32_e32 v1, v28, v35
	v_fma_mix_f32 v1, v1, s76, -v44 op_sel:[0,0,1] op_sel_hi:[0,0,1]
	v_fma_mix_f32 v1, v1, v57, v44 op_sel:[0,0,1] op_sel_hi:[0,0,1]
	v_mul_f32_e32 v1, v65, v1
	v_fmac_f32_e32 v0, v1, v1
	v_add_f32_e32 v1, v29, v36
	v_fma_mix_f32 v1, v1, s76, -v45 op_sel_hi:[0,0,1]
	v_fma_mix_f32 v1, v1, v58, v45 op_sel_hi:[0,0,1]
	v_mul_f32_e32 v1, v66, v1
	v_fmac_f32_e32 v0, v1, v1
	v_add_f32_e32 v1, v30, v37
	v_fma_mix_f32 v1, v1, s76, -v45 op_sel:[0,0,1] op_sel_hi:[0,0,1]
	v_fma_mix_f32 v1, v1, v59, v45 op_sel:[0,0,1] op_sel_hi:[0,0,1]
	v_mul_f32_e32 v1, v67, v1
	v_fmac_f32_e32 v0, v1, v1
	s_nop 1
	v_add_f32_dpp v0, v0, v0 quad_perm:[1,0,3,2] row_mask:0xf bank_mask:0xf bound_ctrl:1
	s_nop 1
	v_add_f32_dpp v0, v0, v0 quad_perm:[2,3,0,1] row_mask:0xf bank_mask:0xf bound_ctrl:1
	s_nop 1
	v_mov_b32_dpp v1, v0 row_half_mirror row_mask:0xf bank_mask:0xf bound_ctrl:1
	s_and_saveexec_b64 s[12:13], s[38:39]
	v_add_f32_e32 v0, v0, v1
	v_max_f32_e32 v0, 0x179abe15, v0
	v_rsq_f32_e32 v2, v0
	v_readlane_b32 s0, v253, 15
	v_readlane_b32 s1, v253, 16
	v_mov_b32_e32 v12, v98
	v_ashrrev_i32_e32 v13, 31, v12
	s_nop 0
	v_mad_i64_i32 v[0:1], s[0:1], v41, 24, s[0:1]
	v_lshl_add_u64 v[0:1], v[12:13], 2, v[0:1]
	global_store_dword v[0:1], v2, off
	s_or_b64 exec, exec, s[12:13]
	s_waitcnt vmcnt(15)
	v_cvt_f32_f16_e32 v20, v84
	v_cvt_f32_f16_sdwa v31, v84 dst_sel:DWORD dst_unused:UNUSED_PAD src0_sel:WORD_1
	v_cvt_f32_f16_e32 v32, v85
	v_cvt_f32_f16_sdwa v33, v85 dst_sel:DWORD dst_unused:UNUSED_PAD src0_sel:WORD_1
	v_cvt_f32_f16_e32 v34, v86
	v_cvt_f32_f16_sdwa v35, v86 dst_sel:DWORD dst_unused:UNUSED_PAD src0_sel:WORD_1
	v_cvt_f32_f16_e32 v36, v87
	v_cvt_f32_f16_sdwa v37, v87 dst_sel:DWORD dst_unused:UNUSED_PAD src0_sel:WORD_1
	v_cvt_f32_f16_e32 v13, v80
	v_cvt_f32_f16_sdwa v24, v80 dst_sel:DWORD dst_unused:UNUSED_PAD src0_sel:WORD_1
	v_cvt_f32_f16_e32 v25, v81
	v_cvt_f32_f16_sdwa v26, v81 dst_sel:DWORD dst_unused:UNUSED_PAD src0_sel:WORD_1
	v_cvt_f32_f16_e32 v27, v82
	v_cvt_f32_f16_sdwa v28, v82 dst_sel:DWORD dst_unused:UNUSED_PAD src0_sel:WORD_1
	v_cvt_f32_f16_e32 v29, v83
	v_cvt_f32_f16_sdwa v30, v83 dst_sel:DWORD dst_unused:UNUSED_PAD src0_sel:WORD_1
	v_add_f32_e32 v6, v13, v20
	v_fma_mix_f32 v6, v6, s76, -v76 op_sel_hi:[0,0,1]
	v_fma_mix_f32 v13, v92, v6, v76 op_sel_hi:[0,0,1]
	v_add_f32_e32 v14, v24, v31
	v_fma_mix_f32 v14, v14, s76, -v76 op_sel:[0,0,1] op_sel_hi:[0,0,1]
	v_fma_mix_f32 v0, v93, v14, v76 op_sel:[0,0,1] op_sel_hi:[0,0,1]
	v_mul_f32_e32 v0, v123, v0
	v_mul_f32_e32 v13, v122, v13
	v_mul_f32_e32 v0, v0, v0
	v_fmac_f32_e32 v0, v13, v13
	v_add_f32_e32 v13, v25, v32
	v_fma_mix_f32 v13, v13, s76, -v77 op_sel_hi:[0,0,1]
	v_fma_mix_f32 v13, v94, v13, v77 op_sel_hi:[0,0,1]
	v_mul_f32_e32 v13, v124, v13
	v_fmac_f32_e32 v0, v13, v13
	v_add_f32_e32 v13, v26, v33
	v_fma_mix_f32 v13, v13, s76, -v77 op_sel:[0,0,1] op_sel_hi:[0,0,1]
	v_fma_mix_f32 v1, v13, v95, v77 op_sel:[0,0,1] op_sel_hi:[0,0,1]
	v_mul_f32_e32 v1, v125, v1
	v_fmac_f32_e32 v0, v1, v1
	v_add_f32_e32 v1, v27, v34
	v_fma_mix_f32 v1, v1, s76, -v78 op_sel_hi:[0,0,1]
	v_fma_mix_f32 v1, v1, v88, v78 op_sel_hi:[0,0,1]
	v_mul_f32_e32 v1, v114, v1
	v_fmac_f32_e32 v0, v1, v1
	v_add_f32_e32 v1, v28, v35
	v_fma_mix_f32 v1, v1, s76, -v78 op_sel:[0,0,1] op_sel_hi:[0,0,1]
	v_fma_mix_f32 v1, v1, v89, v78 op_sel:[0,0,1] op_sel_hi:[0,0,1]
	v_mul_f32_e32 v1, v115, v1
	v_fmac_f32_e32 v0, v1, v1
	v_add_f32_e32 v1, v29, v36
	v_fma_mix_f32 v1, v1, s76, -v79 op_sel_hi:[0,0,1]
	v_fma_mix_f32 v1, v1, v90, v79 op_sel_hi:[0,0,1]
	v_mul_f32_e32 v1, v116, v1
	v_fmac_f32_e32 v0, v1, v1
	v_add_f32_e32 v1, v30, v37
	v_fma_mix_f32 v1, v1, s76, -v79 op_sel:[0,0,1] op_sel_hi:[0,0,1]
	v_fma_mix_f32 v1, v1, v91, v79 op_sel:[0,0,1] op_sel_hi:[0,0,1]
	v_mul_f32_e32 v1, v117, v1
	v_fmac_f32_e32 v0, v1, v1
	s_nop 1
	v_add_f32_dpp v0, v0, v0 quad_perm:[1,0,3,2] row_mask:0xf bank_mask:0xf bound_ctrl:1
	s_nop 1
	v_add_f32_dpp v0, v0, v0 quad_perm:[2,3,0,1] row_mask:0xf bank_mask:0xf bound_ctrl:1
	s_nop 1
	v_mov_b32_dpp v1, v0 row_half_mirror row_mask:0xf bank_mask:0xf bound_ctrl:1
	s_and_saveexec_b64 s[12:13], s[38:39]
	v_add_f32_e32 v0, v0, v1
	v_max_f32_e32 v0, 0x179abe15, v0
	v_rsq_f32_e32 v2, v0
	v_readlane_b32 s0, v253, 15
	v_readlane_b32 s1, v253, 16
	v_mov_b32_e32 v12, v100
	v_ashrrev_i32_e32 v13, 31, v12
	s_nop 0
	v_mad_i64_i32 v[0:1], s[0:1], v50, 24, s[0:1]
	v_lshl_add_u64 v[0:1], v[12:13], 2, v[0:1]
	global_store_dword v[0:1], v2, off
	s_or_b64 exec, exec, s[12:13]
	s_waitcnt vmcnt(9)
	v_cvt_f32_f16_e32 v20, v164
	v_cvt_f32_f16_sdwa v31, v164 dst_sel:DWORD dst_unused:UNUSED_PAD src0_sel:WORD_1
	v_cvt_f32_f16_e32 v32, v165
	v_cvt_f32_f16_sdwa v33, v165 dst_sel:DWORD dst_unused:UNUSED_PAD src0_sel:WORD_1
	v_cvt_f32_f16_e32 v34, v166
	v_cvt_f32_f16_sdwa v35, v166 dst_sel:DWORD dst_unused:UNUSED_PAD src0_sel:WORD_1
	v_cvt_f32_f16_e32 v36, v167
	v_cvt_f32_f16_sdwa v37, v167 dst_sel:DWORD dst_unused:UNUSED_PAD src0_sel:WORD_1
	v_cvt_f32_f16_e32 v13, v130
	v_cvt_f32_f16_sdwa v24, v130 dst_sel:DWORD dst_unused:UNUSED_PAD src0_sel:WORD_1
	v_cvt_f32_f16_e32 v25, v131
	v_cvt_f32_f16_sdwa v26, v131 dst_sel:DWORD dst_unused:UNUSED_PAD src0_sel:WORD_1
	v_cvt_f32_f16_e32 v27, v132
	v_cvt_f32_f16_sdwa v28, v132 dst_sel:DWORD dst_unused:UNUSED_PAD src0_sel:WORD_1
	v_cvt_f32_f16_e32 v29, v133
	v_cvt_f32_f16_sdwa v30, v133 dst_sel:DWORD dst_unused:UNUSED_PAD src0_sel:WORD_1
	v_add_f32_e32 v6, v13, v20
	v_fma_mix_f32 v6, v6, s76, -v126 op_sel_hi:[0,0,1]
	v_fma_mix_f32 v13, v172, v6, v126 op_sel_hi:[0,0,1]
	v_add_f32_e32 v14, v24, v31
	v_fma_mix_f32 v14, v14, s76, -v126 op_sel:[0,0,1] op_sel_hi:[0,0,1]
	v_fma_mix_f32 v0, v173, v14, v126 op_sel:[0,0,1] op_sel_hi:[0,0,1]
	v_mul_f32_e32 v0, v181, v0
	v_mul_f32_e32 v13, v180, v13
	v_mul_f32_e32 v0, v0, v0
	v_fmac_f32_e32 v0, v13, v13
	v_add_f32_e32 v13, v25, v32
	v_fma_mix_f32 v13, v13, s76, -v127 op_sel_hi:[0,0,1]
	v_fma_mix_f32 v13, v174, v13, v127 op_sel_hi:[0,0,1]
	v_mul_f32_e32 v13, v182, v13
	v_fmac_f32_e32 v0, v13, v13
	v_add_f32_e32 v13, v26, v33
	v_fma_mix_f32 v13, v13, s76, -v127 op_sel:[0,0,1] op_sel_hi:[0,0,1]
	v_fma_mix_f32 v1, v13, v175, v127 op_sel:[0,0,1] op_sel_hi:[0,0,1]
	v_mul_f32_e32 v1, v183, v1
	v_fmac_f32_e32 v0, v1, v1
	v_add_f32_e32 v1, v27, v34
	v_fma_mix_f32 v1, v1, s76, -v128 op_sel_hi:[0,0,1]
	v_fma_mix_f32 v1, v1, v168, v128 op_sel_hi:[0,0,1]
	v_mul_f32_e32 v1, v176, v1
	v_fmac_f32_e32 v0, v1, v1
	v_add_f32_e32 v1, v28, v35
	v_fma_mix_f32 v1, v1, s76, -v128 op_sel:[0,0,1] op_sel_hi:[0,0,1]
	v_fma_mix_f32 v1, v1, v169, v128 op_sel:[0,0,1] op_sel_hi:[0,0,1]
	v_mul_f32_e32 v1, v177, v1
	v_fmac_f32_e32 v0, v1, v1
	v_add_f32_e32 v1, v29, v36
	v_fma_mix_f32 v1, v1, s76, -v129 op_sel_hi:[0,0,1]
	v_fma_mix_f32 v1, v1, v170, v129 op_sel_hi:[0,0,1]
	v_mul_f32_e32 v1, v178, v1
	v_fmac_f32_e32 v0, v1, v1
	v_add_f32_e32 v1, v30, v37
	v_fma_mix_f32 v1, v1, s76, -v129 op_sel:[0,0,1] op_sel_hi:[0,0,1]
	v_fma_mix_f32 v1, v1, v171, v129 op_sel:[0,0,1] op_sel_hi:[0,0,1]
	v_mul_f32_e32 v1, v179, v1
	v_fmac_f32_e32 v0, v1, v1
	s_nop 1
	v_add_f32_dpp v0, v0, v0 quad_perm:[1,0,3,2] row_mask:0xf bank_mask:0xf bound_ctrl:1
	s_nop 1
	v_add_f32_dpp v0, v0, v0 quad_perm:[2,3,0,1] row_mask:0xf bank_mask:0xf bound_ctrl:1
	s_nop 1
	v_mov_b32_dpp v1, v0 row_half_mirror row_mask:0xf bank_mask:0xf bound_ctrl:1
	s_and_saveexec_b64 s[12:13], s[38:39]
	v_add_f32_e32 v0, v0, v1
	v_max_f32_e32 v0, 0x179abe15, v0
	v_rsq_f32_e32 v2, v0
	v_readlane_b32 s0, v253, 15
	v_readlane_b32 s1, v253, 16
	v_mov_b32_e32 v12, v103
	v_ashrrev_i32_e32 v13, 31, v12
	s_nop 0
	v_mad_i64_i32 v[0:1], s[0:1], v72, 24, s[0:1]
	v_lshl_add_u64 v[0:1], v[12:13], 2, v[0:1]
	global_store_dword v[0:1], v2, off
	s_or_b64 exec, exec, s[12:13]
	s_waitcnt vmcnt(3)
	v_cvt_f32_f16_e32 v20, v204
	v_cvt_f32_f16_sdwa v31, v204 dst_sel:DWORD dst_unused:UNUSED_PAD src0_sel:WORD_1
	v_cvt_f32_f16_e32 v32, v205
	v_cvt_f32_f16_sdwa v33, v205 dst_sel:DWORD dst_unused:UNUSED_PAD src0_sel:WORD_1
	v_cvt_f32_f16_e32 v34, v206
	v_cvt_f32_f16_sdwa v35, v206 dst_sel:DWORD dst_unused:UNUSED_PAD src0_sel:WORD_1
	v_cvt_f32_f16_e32 v36, v207
	v_cvt_f32_f16_sdwa v37, v207 dst_sel:DWORD dst_unused:UNUSED_PAD src0_sel:WORD_1
	v_cvt_f32_f16_e32 v13, v200
	v_cvt_f32_f16_sdwa v24, v200 dst_sel:DWORD dst_unused:UNUSED_PAD src0_sel:WORD_1
	v_cvt_f32_f16_e32 v25, v201
	v_cvt_f32_f16_sdwa v26, v201 dst_sel:DWORD dst_unused:UNUSED_PAD src0_sel:WORD_1
	v_cvt_f32_f16_e32 v27, v202
	v_cvt_f32_f16_sdwa v28, v202 dst_sel:DWORD dst_unused:UNUSED_PAD src0_sel:WORD_1
	v_cvt_f32_f16_e32 v29, v203
	v_cvt_f32_f16_sdwa v30, v203 dst_sel:DWORD dst_unused:UNUSED_PAD src0_sel:WORD_1
	v_add_f32_e32 v6, v13, v20
	v_fma_mix_f32 v6, v6, s76, -v196 op_sel_hi:[0,0,1]
	v_fma_mix_f32 v13, v212, v6, v196 op_sel_hi:[0,0,1]
	v_add_f32_e32 v14, v24, v31
	v_fma_mix_f32 v14, v14, s76, -v196 op_sel:[0,0,1] op_sel_hi:[0,0,1]
	v_fma_mix_f32 v0, v213, v14, v196 op_sel:[0,0,1] op_sel_hi:[0,0,1]
	v_mul_f32_e32 v0, v221, v0
	v_mul_f32_e32 v13, v220, v13
	v_mul_f32_e32 v0, v0, v0
	v_fmac_f32_e32 v0, v13, v13
	v_add_f32_e32 v13, v25, v32
	v_fma_mix_f32 v13, v13, s76, -v197 op_sel_hi:[0,0,1]
	v_fma_mix_f32 v13, v214, v13, v197 op_sel_hi:[0,0,1]
	v_mul_f32_e32 v13, v222, v13
	v_fmac_f32_e32 v0, v13, v13
	v_add_f32_e32 v13, v26, v33
	v_fma_mix_f32 v13, v13, s76, -v197 op_sel:[0,0,1] op_sel_hi:[0,0,1]
	v_fma_mix_f32 v1, v13, v215, v197 op_sel:[0,0,1] op_sel_hi:[0,0,1]
	v_mul_f32_e32 v1, v223, v1
	v_fmac_f32_e32 v0, v1, v1
	v_add_f32_e32 v1, v27, v34
	v_fma_mix_f32 v1, v1, s76, -v198 op_sel_hi:[0,0,1]
	v_fma_mix_f32 v1, v1, v208, v198 op_sel_hi:[0,0,1]
	v_mul_f32_e32 v1, v216, v1
	v_fmac_f32_e32 v0, v1, v1
	v_add_f32_e32 v1, v28, v35
	v_fma_mix_f32 v1, v1, s76, -v198 op_sel:[0,0,1] op_sel_hi:[0,0,1]
	v_fma_mix_f32 v1, v1, v209, v198 op_sel:[0,0,1] op_sel_hi:[0,0,1]
	v_mul_f32_e32 v1, v217, v1
	v_fmac_f32_e32 v0, v1, v1
	v_add_f32_e32 v1, v29, v36
	v_fma_mix_f32 v1, v1, s76, -v199 op_sel_hi:[0,0,1]
	v_fma_mix_f32 v1, v1, v210, v199 op_sel_hi:[0,0,1]
	v_mul_f32_e32 v1, v218, v1
	v_fmac_f32_e32 v0, v1, v1
	v_add_f32_e32 v1, v30, v37
	v_fma_mix_f32 v1, v1, s76, -v199 op_sel:[0,0,1] op_sel_hi:[0,0,1]
	v_fma_mix_f32 v1, v1, v211, v199 op_sel:[0,0,1] op_sel_hi:[0,0,1]
	v_mul_f32_e32 v1, v219, v1
	v_fmac_f32_e32 v0, v1, v1
	s_nop 1
	v_add_f32_dpp v0, v0, v0 quad_perm:[1,0,3,2] row_mask:0xf bank_mask:0xf bound_ctrl:1
	s_nop 1
	v_add_f32_dpp v0, v0, v0 quad_perm:[2,3,0,1] row_mask:0xf bank_mask:0xf bound_ctrl:1
	s_nop 1
	v_mov_b32_dpp v1, v0 row_half_mirror row_mask:0xf bank_mask:0xf bound_ctrl:1
	s_and_saveexec_b64 s[12:13], s[38:39]
	v_add_f32_e32 v0, v0, v1
	v_max_f32_e32 v0, 0x179abe15, v0
	v_rsq_f32_e32 v2, v0
	v_readlane_b32 s0, v253, 15
	v_readlane_b32 s1, v253, 16
	v_mov_b32_e32 v12, v107
	v_ashrrev_i32_e32 v13, 31, v12
	s_nop 0
	v_mad_i64_i32 v[0:1], s[0:1], v75, 24, s[0:1]
	v_lshl_add_u64 v[0:1], v[12:13], 2, v[0:1]
	global_store_dword v[0:1], v2, off
	s_or_b64 exec, exec, s[12:13]
	s_lshl_b32 s100, s87, 2
	v_add_u32_e32 v40, s100, v40
	s_branch .Linv_top

.Linv_test:
	s_mov_b32 s0, 0x17ffff
	v_cmp_lt_i32_e32 vcc, s0, v40
	s_or_b64 s[6:7], vcc, s[6:7]
	s_andn2_b64 exec, exec, s[6:7]
	s_cbranch_execz .LBB0_699
